# cv8 + G1/G5 first K-iteration of non-first tiles waits vmcnt(24) instead of 8 (epilogue stores and pre loads no longer block the restart)
# baseline (speedup 1.0000x reference)
.LBB0_306:
	s_add_u32 s38, s36, 0xfff80080
	s_addc_u32 s39, s37, -1
	s_add_i32 s45, 0, 0x10000
	s_cmp_eq_u32 s27, 28
	s_cselect_b32 s43, s9, s39
	s_cselect_b32 s42, s14, s38
	v_add_u32_e32 v34, s45, v170
	s_cselect_b32 s39, s16, s26
	s_cselect_b32 s38, s17, s25
	s_add_i32 s47, 0, 0x14000
	ds_read_b128 v[160:163], v34
	ds_read_b128 v[164:167], v34 offset:1024
	ds_read_b128 v[174:177], v34 offset:2048
	ds_read_b128 v[184:187], v34 offset:3072
	v_add_u32_e32 v34, s47, v170
	ds_read_b128 v[188:191], v34
	ds_read_b128 v[192:195], v34 offset:1024
	ds_read_b128 v[196:199], v34 offset:2048
	ds_read_b128 v[200:203], v34 offset:3072
	v_lshl_add_u64 v[168:169], s[36:37], 0, v[152:153]
	s_add_i32 m0, s35, 0xc000
	ds_read_b128 v[214:217], v173
	ds_read_b128 v[218:221], v173 offset:1024
	ds_read_b128 v[222:225], v173 offset:2048
	ds_read_b128 v[226:229], v173 offset:3072
	ds_read_b128 v[230:233], v173 offset:4096
	ds_read_b128 v[234:237], v173 offset:5120
	ds_read_b128 v[238:241], v173 offset:6144
	ds_read_b128 v[242:245], v173 offset:7168
	global_load_lds_dwordx4 v[168:169], off
	v_lshl_add_u64 v[168:169], s[36:37], 0, v[156:157]
	s_add_i32 m0, s35, 0xe000
	s_nop 0
	global_load_lds_dwordx4 v[168:169], off
	s_cmp_eq_u32 s27, -2
	s_cselect_b32 s98, s65, 0
	s_cmp_gt_u32 s98, 1
	s_cbranch_scc1 .Lrlx_g1_0
	s_waitcnt vmcnt(8)
	s_branch .Lrlx_g1_0d
.Lrlx_g1_0:
	s_waitcnt vmcnt(24)
.Lrlx_g1_0d:
	s_waitcnt lgkmcnt(0)
	s_barrier
	s_setprio 1
	s_waitcnt lgkmcnt(0)
	v_mfma_f32_16x16x32_bf16 v[132:135], v[160:163], v[214:217], v[132:135]
	v_mfma_f32_16x16x32_bf16 v[128:131], v[174:177], v[214:217], v[128:131]
	v_mfma_f32_16x16x32_bf16 v[116:119], v[160:163], v[222:225], v[116:119]
	v_mfma_f32_16x16x32_bf16 v[112:115], v[174:177], v[222:225], v[112:115]
	v_mfma_f32_16x16x32_bf16 v[100:103], v[160:163], v[230:233], v[100:103]
	v_mfma_f32_16x16x32_bf16 v[96:99], v[174:177], v[230:233], v[96:99]
	v_mfma_f32_16x16x32_bf16 v[84:87], v[160:163], v[238:241], v[84:87]
	v_mfma_f32_16x16x32_bf16 v[80:83], v[174:177], v[238:241], v[80:83]
	v_mfma_f32_16x16x32_bf16 v[132:135], v[164:167], v[218:221], v[132:135]
	v_mfma_f32_16x16x32_bf16 v[128:131], v[184:187], v[218:221], v[128:131]
	v_mfma_f32_16x16x32_bf16 v[116:119], v[164:167], v[226:229], v[116:119]
	v_mfma_f32_16x16x32_bf16 v[112:115], v[184:187], v[226:229], v[112:115]
	v_mfma_f32_16x16x32_bf16 v[100:103], v[164:167], v[234:237], v[100:103]
	v_mfma_f32_16x16x32_bf16 v[96:99], v[184:187], v[234:237], v[96:99]
	v_mfma_f32_16x16x32_bf16 v[84:87], v[164:167], v[242:245], v[84:87]
	v_mfma_f32_16x16x32_bf16 v[80:83], v[184:187], v[242:245], v[80:83]
	s_setprio 0
	s_setprio 1
	v_mfma_f32_16x16x32_bf16 v[124:127], v[188:191], v[214:217], v[124:127]
	v_mfma_f32_16x16x32_bf16 v[120:123], v[196:199], v[214:217], v[120:123]
	v_mfma_f32_16x16x32_bf16 v[108:111], v[188:191], v[222:225], v[108:111]
	v_mfma_f32_16x16x32_bf16 v[104:107], v[196:199], v[222:225], v[104:107]
	v_mfma_f32_16x16x32_bf16 v[92:95], v[188:191], v[230:233], v[92:95]
	v_mfma_f32_16x16x32_bf16 v[88:91], v[196:199], v[230:233], v[88:91]
	v_mfma_f32_16x16x32_bf16 v[76:79], v[188:191], v[238:241], v[76:79]
	v_mfma_f32_16x16x32_bf16 v[72:75], v[196:199], v[238:241], v[72:75]
	v_mfma_f32_16x16x32_bf16 v[124:127], v[192:195], v[218:221], v[124:127]
	v_mfma_f32_16x16x32_bf16 v[120:123], v[200:203], v[218:221], v[120:123]
	v_mfma_f32_16x16x32_bf16 v[108:111], v[192:195], v[226:229], v[108:111]
	v_mfma_f32_16x16x32_bf16 v[104:107], v[200:203], v[226:229], v[104:107]
	v_mfma_f32_16x16x32_bf16 v[92:95], v[192:195], v[234:237], v[92:95]
	v_mfma_f32_16x16x32_bf16 v[88:91], v[200:203], v[234:237], v[88:91]
	v_mfma_f32_16x16x32_bf16 v[76:79], v[192:195], v[242:245], v[76:79]
	v_mfma_f32_16x16x32_bf16 v[72:75], v[200:203], v[242:245], v[72:75]
	s_setprio 0
	s_barrier
	s_add_i32 s45, s45, s53
	v_lshl_add_u64 v[168:169], s[38:39], 0, v[136:137]
	s_mov_b32 m0, s45
	ds_read_b128 v[214:217], v173 offset:16384
	ds_read_b128 v[218:221], v173 offset:17408
	ds_read_b128 v[222:225], v173 offset:18432
	ds_read_b128 v[226:229], v173 offset:19456
	ds_read_b128 v[230:233], v173 offset:20480
	ds_read_b128 v[234:237], v173 offset:21504
	ds_read_b128 v[238:241], v173 offset:22528
	ds_read_b128 v[242:245], v173 offset:23552
	global_load_lds_dwordx4 v[168:169], off
	s_add_i32 m0, s45, 0x2000
	s_add_u32 s70, s38, 0x80000
	v_lshl_add_u64 v[204:205], s[38:39], 0, v[140:141]
	s_addc_u32 s71, s39, 0
	s_add_i32 s45, s47, s53
	global_load_lds_dwordx4 v[204:205], off
	v_lshl_add_u64 v[246:247], s[70:71], 0, v[136:137]
	s_mov_b32 m0, s45
	v_lshl_add_u64 v[248:249], s[42:43], 0, v[138:139]
	global_load_lds_dwordx4 v[246:247], off
	v_lshl_add_u64 v[246:247], s[70:71], 0, v[140:141]
	s_add_i32 m0, s45, 0x2000
	s_nop 0
	global_load_lds_dwordx4 v[246:247], off
	v_lshl_add_u64 v[246:247], s[42:43], 0, v[14:15]
	s_mov_b32 m0, s35
	s_nop 0
	global_load_lds_dwordx4 v[246:247], off
	s_mov_b32 m0, s54
	s_nop 0
	global_load_lds_dwordx4 v[248:249], off
	s_cmp_eq_u32 s27, -2
	s_cselect_b32 s98, s65, 0
	s_cmp_gt_u32 s98, 1
	s_cbranch_scc1 .Lrlx_g1_1
	s_waitcnt vmcnt(8)
	s_branch .Lrlx_g1_1d

.Lrlx_g1_1d:
	s_waitcnt lgkmcnt(0)
	s_barrier
	s_setprio 1
	s_waitcnt lgkmcnt(0)
	v_mfma_f32_16x16x32_bf16 v[68:71], v[160:163], v[214:217], v[68:71]
	v_mfma_f32_16x16x32_bf16 v[64:67], v[174:177], v[214:217], v[64:67]
	v_mfma_f32_16x16x32_bf16 v[52:55], v[160:163], v[222:225], v[52:55]
	v_mfma_f32_16x16x32_bf16 v[48:51], v[174:177], v[222:225], v[48:51]
	v_mfma_f32_16x16x32_bf16 v[36:39], v[160:163], v[230:233], v[36:39]
	v_mfma_f32_16x16x32_bf16 v[30:33], v[174:177], v[230:233], v[30:33]
	v_mfma_f32_16x16x32_bf16 v[18:21], v[160:163], v[238:241], v[18:21]
	v_mfma_f32_16x16x32_bf16 v[10:13], v[174:177], v[238:241], v[10:13]
	v_mfma_f32_16x16x32_bf16 v[68:71], v[164:167], v[218:221], v[68:71]
	v_mfma_f32_16x16x32_bf16 v[64:67], v[184:187], v[218:221], v[64:67]
	v_mfma_f32_16x16x32_bf16 v[52:55], v[164:167], v[226:229], v[52:55]
	v_mfma_f32_16x16x32_bf16 v[48:51], v[184:187], v[226:229], v[48:51]
	v_mfma_f32_16x16x32_bf16 v[36:39], v[164:167], v[234:237], v[36:39]
	v_mfma_f32_16x16x32_bf16 v[30:33], v[184:187], v[234:237], v[30:33]
	v_mfma_f32_16x16x32_bf16 v[18:21], v[164:167], v[242:245], v[18:21]
	v_mfma_f32_16x16x32_bf16 v[10:13], v[184:187], v[242:245], v[10:13]
	s_setprio 0
	s_setprio 1
	v_mfma_f32_16x16x32_bf16 v[60:63], v[188:191], v[214:217], v[60:63]
	v_mfma_f32_16x16x32_bf16 v[56:59], v[196:199], v[214:217], v[56:59]
	v_mfma_f32_16x16x32_bf16 v[44:47], v[188:191], v[222:225], v[44:47]
	v_mfma_f32_16x16x32_bf16 v[40:43], v[196:199], v[222:225], v[40:43]
	v_mfma_f32_16x16x32_bf16 v[26:29], v[188:191], v[230:233], v[26:29]
	v_mfma_f32_16x16x32_bf16 v[22:25], v[196:199], v[230:233], v[22:25]
	v_mfma_f32_16x16x32_bf16 v[6:9], v[188:191], v[238:241], v[6:9]
	v_mfma_f32_16x16x32_bf16 v[2:5], v[196:199], v[238:241], v[2:5]
	v_mfma_f32_16x16x32_bf16 v[60:63], v[192:195], v[218:221], v[60:63]
	v_mfma_f32_16x16x32_bf16 v[56:59], v[200:203], v[218:221], v[56:59]
	v_mfma_f32_16x16x32_bf16 v[44:47], v[192:195], v[226:229], v[44:47]
	v_mfma_f32_16x16x32_bf16 v[40:43], v[200:203], v[226:229], v[40:43]
	v_mfma_f32_16x16x32_bf16 v[26:29], v[192:195], v[234:237], v[26:29]
	v_mfma_f32_16x16x32_bf16 v[22:25], v[200:203], v[234:237], v[22:25]
	v_mfma_f32_16x16x32_bf16 v[6:9], v[192:195], v[242:245], v[6:9]
	v_mfma_f32_16x16x32_bf16 v[2:5], v[200:203], v[242:245], v[2:5]
	s_setprio 0
	s_barrier
	s_add_i32 s45, 0, 0x18000
	v_add_u32_e32 v34, s45, v170
	s_add_i32 s47, 0, 0x1c000
	ds_read_b128 v[160:163], v34
	ds_read_b128 v[164:167], v34 offset:1024
	ds_read_b128 v[174:177], v34 offset:2048
	ds_read_b128 v[184:187], v34 offset:3072
	v_add_u32_e32 v34, s47, v170
	ds_read_b128 v[188:191], v34
	ds_read_b128 v[192:195], v34 offset:1024
	ds_read_b128 v[196:199], v34 offset:2048
	ds_read_b128 v[200:203], v34 offset:3072
	s_add_u32 s42, s42, 0x80000
	s_addc_u32 s43, s43, 0
	s_mov_b32 m0, s55
	v_lshl_add_u64 v[250:251], s[42:43], 0, v[14:15]
	ds_read_b128 v[214:217], v173 offset:32768
	ds_read_b128 v[218:221], v173 offset:33792
	ds_read_b128 v[222:225], v173 offset:34816
	ds_read_b128 v[226:229], v173 offset:35840
	ds_read_b128 v[230:233], v173 offset:36864
	ds_read_b128 v[234:237], v173 offset:37888
	ds_read_b128 v[238:241], v173 offset:38912
	ds_read_b128 v[242:245], v173 offset:39936
	global_load_lds_dwordx4 v[250:251], off
	v_lshl_add_u64 v[250:251], s[42:43], 0, v[138:139]
	s_mov_b32 m0, s60
	s_nop 0
	global_load_lds_dwordx4 v[250:251], off
	s_waitcnt vmcnt(8)
	s_waitcnt lgkmcnt(0)
	s_barrier
	s_setprio 1
	s_waitcnt lgkmcnt(0)
	v_mfma_f32_16x16x32_bf16 v[132:135], v[160:163], v[214:217], v[132:135]
	v_mfma_f32_16x16x32_bf16 v[128:131], v[174:177], v[214:217], v[128:131]
	v_mfma_f32_16x16x32_bf16 v[116:119], v[160:163], v[222:225], v[116:119]
	v_mfma_f32_16x16x32_bf16 v[112:115], v[174:177], v[222:225], v[112:115]
	v_mfma_f32_16x16x32_bf16 v[100:103], v[160:163], v[230:233], v[100:103]
	v_mfma_f32_16x16x32_bf16 v[96:99], v[174:177], v[230:233], v[96:99]
	v_mfma_f32_16x16x32_bf16 v[84:87], v[160:163], v[238:241], v[84:87]
	v_mfma_f32_16x16x32_bf16 v[80:83], v[174:177], v[238:241], v[80:83]
	v_mfma_f32_16x16x32_bf16 v[132:135], v[164:167], v[218:221], v[132:135]
	v_mfma_f32_16x16x32_bf16 v[128:131], v[184:187], v[218:221], v[128:131]
	v_mfma_f32_16x16x32_bf16 v[116:119], v[164:167], v[226:229], v[116:119]
	v_mfma_f32_16x16x32_bf16 v[112:115], v[184:187], v[226:229], v[112:115]
	v_mfma_f32_16x16x32_bf16 v[100:103], v[164:167], v[234:237], v[100:103]
	v_mfma_f32_16x16x32_bf16 v[96:99], v[184:187], v[234:237], v[96:99]
	v_mfma_f32_16x16x32_bf16 v[84:87], v[164:167], v[242:245], v[84:87]
	v_mfma_f32_16x16x32_bf16 v[80:83], v[184:187], v[242:245], v[80:83]
	s_setprio 0
	s_setprio 1
	v_mfma_f32_16x16x32_bf16 v[124:127], v[188:191], v[214:217], v[124:127]
	v_mfma_f32_16x16x32_bf16 v[120:123], v[196:199], v[214:217], v[120:123]
	v_mfma_f32_16x16x32_bf16 v[108:111], v[188:191], v[222:225], v[108:111]
	v_mfma_f32_16x16x32_bf16 v[104:107], v[196:199], v[222:225], v[104:107]
	v_mfma_f32_16x16x32_bf16 v[92:95], v[188:191], v[230:233], v[92:95]
	v_mfma_f32_16x16x32_bf16 v[88:91], v[196:199], v[230:233], v[88:91]
	v_mfma_f32_16x16x32_bf16 v[76:79], v[188:191], v[238:241], v[76:79]
	v_mfma_f32_16x16x32_bf16 v[72:75], v[196:199], v[238:241], v[72:75]
	v_mfma_f32_16x16x32_bf16 v[124:127], v[192:195], v[218:221], v[124:127]
	v_mfma_f32_16x16x32_bf16 v[120:123], v[200:203], v[218:221], v[120:123]
	v_mfma_f32_16x16x32_bf16 v[108:111], v[192:195], v[226:229], v[108:111]
	v_mfma_f32_16x16x32_bf16 v[104:107], v[200:203], v[226:229], v[104:107]
	v_mfma_f32_16x16x32_bf16 v[92:95], v[192:195], v[234:237], v[92:95]
	v_mfma_f32_16x16x32_bf16 v[88:91], v[200:203], v[234:237], v[88:91]
	v_mfma_f32_16x16x32_bf16 v[76:79], v[192:195], v[242:245], v[76:79]
	v_mfma_f32_16x16x32_bf16 v[72:75], v[200:203], v[242:245], v[72:75]
	s_setprio 0
	s_barrier
	s_add_i32 s42, s45, s53
	v_lshl_add_u64 v[168:169], v[168:169], 0, s[22:23]
	s_mov_b32 m0, s42
	ds_read_b128 v[214:217], v173 offset:49152
	ds_read_b128 v[218:221], v173 offset:50176
	ds_read_b128 v[222:225], v173 offset:51200
	ds_read_b128 v[226:229], v173 offset:52224
	ds_read_b128 v[230:233], v173 offset:53248
	ds_read_b128 v[234:237], v173 offset:54272
	ds_read_b128 v[238:241], v173 offset:55296
	ds_read_b128 v[242:245], v173 offset:56320
	global_load_lds_dwordx4 v[168:169], off
	s_add_i32 m0, s42, 0x2000
	s_add_u32 s38, s38, 0x80080
	v_lshl_add_u64 v[168:169], v[204:205], 0, s[22:23]
	s_addc_u32 s39, s39, 0
	s_add_i32 s42, s47, s53
	global_load_lds_dwordx4 v[168:169], off
	v_lshl_add_u64 v[168:169], s[38:39], 0, v[136:137]
	s_mov_b32 m0, s42
	s_nop 0
	global_load_lds_dwordx4 v[168:169], off
	v_lshl_add_u64 v[168:169], s[38:39], 0, v[140:141]
	s_add_i32 m0, s42, 0x2000
	s_nop 0
	global_load_lds_dwordx4 v[168:169], off
	v_lshl_add_u64 v[168:169], v[246:247], 0, s[22:23]
	s_mov_b32 m0, s61
	s_nop 0
	global_load_lds_dwordx4 v[168:169], off
	v_lshl_add_u64 v[168:169], v[248:249], 0, s[22:23]
	s_mov_b32 m0, s64
	s_nop 0
	global_load_lds_dwordx4 v[168:169], off
	s_waitcnt vmcnt(8)
	s_waitcnt lgkmcnt(0)
	s_barrier
	s_setprio 1
	s_waitcnt lgkmcnt(0)
	v_mfma_f32_16x16x32_bf16 v[68:71], v[160:163], v[214:217], v[68:71]
	v_mfma_f32_16x16x32_bf16 v[64:67], v[174:177], v[214:217], v[64:67]
	v_mfma_f32_16x16x32_bf16 v[52:55], v[160:163], v[222:225], v[52:55]
	v_mfma_f32_16x16x32_bf16 v[48:51], v[174:177], v[222:225], v[48:51]
	v_mfma_f32_16x16x32_bf16 v[36:39], v[160:163], v[230:233], v[36:39]
	v_mfma_f32_16x16x32_bf16 v[30:33], v[174:177], v[230:233], v[30:33]
	v_mfma_f32_16x16x32_bf16 v[18:21], v[160:163], v[238:241], v[18:21]
	v_mfma_f32_16x16x32_bf16 v[10:13], v[174:177], v[238:241], v[10:13]
	v_mfma_f32_16x16x32_bf16 v[68:71], v[164:167], v[218:221], v[68:71]
	v_mfma_f32_16x16x32_bf16 v[64:67], v[184:187], v[218:221], v[64:67]
	v_mfma_f32_16x16x32_bf16 v[52:55], v[164:167], v[226:229], v[52:55]
	v_mfma_f32_16x16x32_bf16 v[48:51], v[184:187], v[226:229], v[48:51]
	v_mfma_f32_16x16x32_bf16 v[36:39], v[164:167], v[234:237], v[36:39]
	v_mfma_f32_16x16x32_bf16 v[30:33], v[184:187], v[234:237], v[30:33]
	v_mfma_f32_16x16x32_bf16 v[18:21], v[164:167], v[242:245], v[18:21]
	v_mfma_f32_16x16x32_bf16 v[10:13], v[184:187], v[242:245], v[10:13]
	s_setprio 0
	s_setprio 1
	v_mfma_f32_16x16x32_bf16 v[60:63], v[188:191], v[214:217], v[60:63]
	v_mfma_f32_16x16x32_bf16 v[56:59], v[196:199], v[214:217], v[56:59]
	v_mfma_f32_16x16x32_bf16 v[44:47], v[188:191], v[222:225], v[44:47]
	v_mfma_f32_16x16x32_bf16 v[40:43], v[196:199], v[222:225], v[40:43]
	v_mfma_f32_16x16x32_bf16 v[26:29], v[188:191], v[230:233], v[26:29]
	v_mfma_f32_16x16x32_bf16 v[22:25], v[196:199], v[230:233], v[22:25]
	v_mfma_f32_16x16x32_bf16 v[6:9], v[188:191], v[238:241], v[6:9]
	v_mfma_f32_16x16x32_bf16 v[2:5], v[196:199], v[238:241], v[2:5]
	v_mfma_f32_16x16x32_bf16 v[60:63], v[192:195], v[218:221], v[60:63]
	v_mfma_f32_16x16x32_bf16 v[56:59], v[200:203], v[218:221], v[56:59]
	v_mfma_f32_16x16x32_bf16 v[44:47], v[192:195], v[226:229], v[44:47]
	v_mfma_f32_16x16x32_bf16 v[40:43], v[200:203], v[226:229], v[40:43]
	v_mfma_f32_16x16x32_bf16 v[26:29], v[192:195], v[234:237], v[26:29]
	v_mfma_f32_16x16x32_bf16 v[22:25], v[200:203], v[234:237], v[22:25]
	v_mfma_f32_16x16x32_bf16 v[6:9], v[192:195], v[242:245], v[6:9]
	v_mfma_f32_16x16x32_bf16 v[2:5], v[200:203], v[242:245], v[2:5]
	s_setprio 0
	s_barrier
	s_add_i32 s27, s27, 2
	s_add_u32 s36, s36, 0x100
	s_addc_u32 s37, s37, 0
	s_add_u32 s25, s25, 0x100
	s_addc_u32 s26, s26, 0
	s_cmp_gt_u32 s27, 29
	s_cbranch_scc0 .LBB0_306
	s_and_b64 vcc, exec, s[28:29]
	s_cbranch_vccz .LBB0_309
	s_barrier

.LBB0_1664:
	s_add_u32 s44, s42, 0xfff80080
	s_addc_u32 s45, s43, -1
	s_add_i32 s64, 0, 0x10000
	s_cmp_eq_u32 s61, 28
	s_cselect_b32 s47, s29, s45
	s_cselect_b32 s46, s53, s44
	v_add_u32_e32 v151, s64, v141
	s_cselect_b32 s45, s13, s60
	s_cselect_b32 s44, s54, s55
	s_add_i32 s67, 0, 0x14000
	ds_read_b128 v[162:165], v151
	ds_read_b128 v[166:169], v151 offset:1024
	ds_read_b128 v[170:173], v151 offset:2048
	ds_read_b128 v[174:177], v151 offset:3072
	v_add_u32_e32 v151, s67, v141
	ds_read_b128 v[184:187], v151
	ds_read_b128 v[188:191], v151 offset:1024
	ds_read_b128 v[192:195], v151 offset:2048
	ds_read_b128 v[196:199], v151 offset:3072
	v_lshl_add_u64 v[158:159], s[42:43], 0, v[142:143]
	s_add_i32 m0, s25, 0xc000
	ds_read_b128 v[200:203], v149
	ds_read_b128 v[214:217], v149 offset:1024
	ds_read_b128 v[218:221], v149 offset:2048
	ds_read_b128 v[222:225], v149 offset:3072
	ds_read_b128 v[226:229], v149 offset:4096
	ds_read_b128 v[230:233], v149 offset:5120
	ds_read_b128 v[234:237], v149 offset:6144
	ds_read_b128 v[238:241], v149 offset:7168
	global_load_lds_dwordx4 v[158:159], off
	v_lshl_add_u64 v[158:159], s[42:43], 0, v[144:145]
	s_add_i32 m0, s25, 0xe000
	s_nop 0
	global_load_lds_dwordx4 v[158:159], off
	s_cmp_eq_u32 s61, -2
	s_cselect_b32 s98, s50, 0
	s_cmp_gt_u32 s98, 1
	s_cbranch_scc1 .Lrlx_g5_0
	s_waitcnt vmcnt(8)
	s_branch .Lrlx_g5_0d

.Lrlx_g5_0d:
	s_waitcnt lgkmcnt(0)
	s_barrier
	s_setprio 1
	s_waitcnt lgkmcnt(0)
	v_mfma_f32_16x16x32_bf16 v[132:135], v[162:165], v[200:203], v[132:135]
	v_mfma_f32_16x16x32_bf16 v[128:131], v[170:173], v[200:203], v[128:131]
	v_mfma_f32_16x16x32_bf16 v[116:119], v[162:165], v[218:221], v[116:119]
	v_mfma_f32_16x16x32_bf16 v[112:115], v[170:173], v[218:221], v[112:115]
	v_mfma_f32_16x16x32_bf16 v[100:103], v[162:165], v[226:229], v[100:103]
	v_mfma_f32_16x16x32_bf16 v[96:99], v[170:173], v[226:229], v[96:99]
	v_mfma_f32_16x16x32_bf16 v[84:87], v[162:165], v[234:237], v[84:87]
	v_mfma_f32_16x16x32_bf16 v[80:83], v[170:173], v[234:237], v[80:83]
	v_mfma_f32_16x16x32_bf16 v[132:135], v[166:169], v[214:217], v[132:135]
	v_mfma_f32_16x16x32_bf16 v[128:131], v[174:177], v[214:217], v[128:131]
	v_mfma_f32_16x16x32_bf16 v[116:119], v[166:169], v[222:225], v[116:119]
	v_mfma_f32_16x16x32_bf16 v[112:115], v[174:177], v[222:225], v[112:115]
	v_mfma_f32_16x16x32_bf16 v[100:103], v[166:169], v[230:233], v[100:103]
	v_mfma_f32_16x16x32_bf16 v[96:99], v[174:177], v[230:233], v[96:99]
	v_mfma_f32_16x16x32_bf16 v[84:87], v[166:169], v[238:241], v[84:87]
	v_mfma_f32_16x16x32_bf16 v[80:83], v[174:177], v[238:241], v[80:83]
	s_setprio 0
	s_setprio 1
	v_mfma_f32_16x16x32_bf16 v[124:127], v[184:187], v[200:203], v[124:127]
	v_mfma_f32_16x16x32_bf16 v[120:123], v[192:195], v[200:203], v[120:123]
	v_mfma_f32_16x16x32_bf16 v[108:111], v[184:187], v[218:221], v[108:111]
	v_mfma_f32_16x16x32_bf16 v[104:107], v[192:195], v[218:221], v[104:107]
	v_mfma_f32_16x16x32_bf16 v[92:95], v[184:187], v[226:229], v[92:95]
	v_mfma_f32_16x16x32_bf16 v[88:91], v[192:195], v[226:229], v[88:91]
	v_mfma_f32_16x16x32_bf16 v[76:79], v[184:187], v[234:237], v[76:79]
	v_mfma_f32_16x16x32_bf16 v[72:75], v[192:195], v[234:237], v[72:75]
	v_mfma_f32_16x16x32_bf16 v[124:127], v[188:191], v[214:217], v[124:127]
	v_mfma_f32_16x16x32_bf16 v[120:123], v[196:199], v[214:217], v[120:123]
	v_mfma_f32_16x16x32_bf16 v[108:111], v[188:191], v[222:225], v[108:111]
	v_mfma_f32_16x16x32_bf16 v[104:107], v[196:199], v[222:225], v[104:107]
	v_mfma_f32_16x16x32_bf16 v[92:95], v[188:191], v[230:233], v[92:95]
	v_mfma_f32_16x16x32_bf16 v[88:91], v[196:199], v[230:233], v[88:91]
	v_mfma_f32_16x16x32_bf16 v[76:79], v[188:191], v[238:241], v[76:79]
	v_mfma_f32_16x16x32_bf16 v[72:75], v[196:199], v[238:241], v[72:75]
	s_setprio 0
	s_barrier
	s_add_i32 s64, s64, s20
	v_lshl_add_u64 v[158:159], s[44:45], 0, v[34:35]
	s_mov_b32 m0, s64
	ds_read_b128 v[200:203], v149 offset:16384
	ds_read_b128 v[214:217], v149 offset:17408
	ds_read_b128 v[218:221], v149 offset:18432
	ds_read_b128 v[222:225], v149 offset:19456
	ds_read_b128 v[226:229], v149 offset:20480
	ds_read_b128 v[230:233], v149 offset:21504
	ds_read_b128 v[234:237], v149 offset:22528
	ds_read_b128 v[238:241], v149 offset:23552
	global_load_lds_dwordx4 v[158:159], off
	s_add_i32 m0, s64, 0x2000
	s_add_u32 s64, s44, 0x80000
	v_lshl_add_u64 v[204:205], s[44:45], 0, v[14:15]
	s_addc_u32 s65, s45, 0
	s_add_i32 s67, s67, s20
	global_load_lds_dwordx4 v[204:205], off
	v_lshl_add_u64 v[242:243], s[64:65], 0, v[34:35]
	s_mov_b32 m0, s67
	v_lshl_add_u64 v[244:245], s[46:47], 0, v[136:137]
	global_load_lds_dwordx4 v[242:243], off
	v_lshl_add_u64 v[242:243], s[64:65], 0, v[14:15]
	s_add_i32 m0, s67, 0x2000
	s_nop 0
	global_load_lds_dwordx4 v[242:243], off
	v_lshl_add_u64 v[242:243], s[46:47], 0, v[138:139]
	s_mov_b32 m0, s25
	s_nop 0
	global_load_lds_dwordx4 v[242:243], off
	s_mov_b32 m0, s26
	s_nop 0
	global_load_lds_dwordx4 v[244:245], off
	s_cmp_eq_u32 s61, -2
	s_cselect_b32 s98, s50, 0
	s_cmp_gt_u32 s98, 1
	s_cbranch_scc1 .Lrlx_g5_1
	s_waitcnt vmcnt(8)
	s_branch .Lrlx_g5_1d

.Lrlx_g5_1d:
	s_waitcnt lgkmcnt(0)
	s_barrier
	s_setprio 1
	s_waitcnt lgkmcnt(0)
	v_mfma_f32_16x16x32_bf16 v[68:71], v[162:165], v[200:203], v[68:71]
	v_mfma_f32_16x16x32_bf16 v[64:67], v[170:173], v[200:203], v[64:67]
	v_mfma_f32_16x16x32_bf16 v[52:55], v[162:165], v[218:221], v[52:55]
	v_mfma_f32_16x16x32_bf16 v[48:51], v[170:173], v[218:221], v[48:51]
	v_mfma_f32_16x16x32_bf16 v[36:39], v[162:165], v[226:229], v[36:39]
	v_mfma_f32_16x16x32_bf16 v[30:33], v[170:173], v[226:229], v[30:33]
	v_mfma_f32_16x16x32_bf16 v[18:21], v[162:165], v[234:237], v[18:21]
	v_mfma_f32_16x16x32_bf16 v[10:13], v[170:173], v[234:237], v[10:13]
	v_mfma_f32_16x16x32_bf16 v[68:71], v[166:169], v[214:217], v[68:71]
	v_mfma_f32_16x16x32_bf16 v[64:67], v[174:177], v[214:217], v[64:67]
	v_mfma_f32_16x16x32_bf16 v[52:55], v[166:169], v[222:225], v[52:55]
	v_mfma_f32_16x16x32_bf16 v[48:51], v[174:177], v[222:225], v[48:51]
	v_mfma_f32_16x16x32_bf16 v[36:39], v[166:169], v[230:233], v[36:39]
	v_mfma_f32_16x16x32_bf16 v[30:33], v[174:177], v[230:233], v[30:33]
	v_mfma_f32_16x16x32_bf16 v[18:21], v[166:169], v[238:241], v[18:21]
	v_mfma_f32_16x16x32_bf16 v[10:13], v[174:177], v[238:241], v[10:13]
	s_setprio 0
	s_setprio 1
	v_mfma_f32_16x16x32_bf16 v[60:63], v[184:187], v[200:203], v[60:63]
	v_mfma_f32_16x16x32_bf16 v[56:59], v[192:195], v[200:203], v[56:59]
	v_mfma_f32_16x16x32_bf16 v[44:47], v[184:187], v[218:221], v[44:47]
	v_mfma_f32_16x16x32_bf16 v[40:43], v[192:195], v[218:221], v[40:43]
	v_mfma_f32_16x16x32_bf16 v[26:29], v[184:187], v[226:229], v[26:29]
	v_mfma_f32_16x16x32_bf16 v[22:25], v[192:195], v[226:229], v[22:25]
	v_mfma_f32_16x16x32_bf16 v[6:9], v[184:187], v[234:237], v[6:9]
	v_mfma_f32_16x16x32_bf16 v[2:5], v[192:195], v[234:237], v[2:5]
	v_mfma_f32_16x16x32_bf16 v[60:63], v[188:191], v[214:217], v[60:63]
	v_mfma_f32_16x16x32_bf16 v[56:59], v[196:199], v[214:217], v[56:59]
	v_mfma_f32_16x16x32_bf16 v[44:47], v[188:191], v[222:225], v[44:47]
	v_mfma_f32_16x16x32_bf16 v[40:43], v[196:199], v[222:225], v[40:43]
	v_mfma_f32_16x16x32_bf16 v[26:29], v[188:191], v[230:233], v[26:29]
	v_mfma_f32_16x16x32_bf16 v[22:25], v[196:199], v[230:233], v[22:25]
	v_mfma_f32_16x16x32_bf16 v[6:9], v[188:191], v[238:241], v[6:9]
	v_mfma_f32_16x16x32_bf16 v[2:5], v[196:199], v[238:241], v[2:5]
	s_setprio 0
	s_barrier
	s_add_i32 s64, 0, 0x18000
	v_add_u32_e32 v151, s64, v141
	s_add_i32 s65, 0, 0x1c000
	ds_read_b128 v[162:165], v151
	ds_read_b128 v[166:169], v151 offset:1024
	ds_read_b128 v[170:173], v151 offset:2048
	ds_read_b128 v[174:177], v151 offset:3072
	v_add_u32_e32 v151, s65, v141
	ds_read_b128 v[184:187], v151
	ds_read_b128 v[188:191], v151 offset:1024
	ds_read_b128 v[192:195], v151 offset:2048
	ds_read_b128 v[196:199], v151 offset:3072
	s_add_u32 s46, s46, 0x80000
	s_addc_u32 s47, s47, 0
	s_mov_b32 m0, s27
	v_lshl_add_u64 v[246:247], s[46:47], 0, v[138:139]
	ds_read_b128 v[200:203], v149 offset:32768
	ds_read_b128 v[214:217], v149 offset:33792
	ds_read_b128 v[218:221], v149 offset:34816
	ds_read_b128 v[222:225], v149 offset:35840
	ds_read_b128 v[226:229], v149 offset:36864
	ds_read_b128 v[230:233], v149 offset:37888
	ds_read_b128 v[234:237], v149 offset:38912
	ds_read_b128 v[238:241], v149 offset:39936
	global_load_lds_dwordx4 v[246:247], off
	v_lshl_add_u64 v[246:247], s[46:47], 0, v[136:137]
	s_mov_b32 m0, s31
	s_nop 0
	global_load_lds_dwordx4 v[246:247], off
	s_waitcnt vmcnt(8)
	s_waitcnt lgkmcnt(0)
	s_barrier
	s_setprio 1
	s_waitcnt lgkmcnt(0)
	v_mfma_f32_16x16x32_bf16 v[132:135], v[162:165], v[200:203], v[132:135]
	v_mfma_f32_16x16x32_bf16 v[128:131], v[170:173], v[200:203], v[128:131]
	v_mfma_f32_16x16x32_bf16 v[116:119], v[162:165], v[218:221], v[116:119]
	v_mfma_f32_16x16x32_bf16 v[112:115], v[170:173], v[218:221], v[112:115]
	v_mfma_f32_16x16x32_bf16 v[100:103], v[162:165], v[226:229], v[100:103]
	v_mfma_f32_16x16x32_bf16 v[96:99], v[170:173], v[226:229], v[96:99]
	v_mfma_f32_16x16x32_bf16 v[84:87], v[162:165], v[234:237], v[84:87]
	v_mfma_f32_16x16x32_bf16 v[80:83], v[170:173], v[234:237], v[80:83]
	v_mfma_f32_16x16x32_bf16 v[132:135], v[166:169], v[214:217], v[132:135]
	v_mfma_f32_16x16x32_bf16 v[128:131], v[174:177], v[214:217], v[128:131]
	v_mfma_f32_16x16x32_bf16 v[116:119], v[166:169], v[222:225], v[116:119]
	v_mfma_f32_16x16x32_bf16 v[112:115], v[174:177], v[222:225], v[112:115]
	v_mfma_f32_16x16x32_bf16 v[100:103], v[166:169], v[230:233], v[100:103]
	v_mfma_f32_16x16x32_bf16 v[96:99], v[174:177], v[230:233], v[96:99]
	v_mfma_f32_16x16x32_bf16 v[84:87], v[166:169], v[238:241], v[84:87]
	v_mfma_f32_16x16x32_bf16 v[80:83], v[174:177], v[238:241], v[80:83]
	s_setprio 0
	s_setprio 1
	v_mfma_f32_16x16x32_bf16 v[124:127], v[184:187], v[200:203], v[124:127]
	v_mfma_f32_16x16x32_bf16 v[120:123], v[192:195], v[200:203], v[120:123]
	v_mfma_f32_16x16x32_bf16 v[108:111], v[184:187], v[218:221], v[108:111]
	v_mfma_f32_16x16x32_bf16 v[104:107], v[192:195], v[218:221], v[104:107]
	v_mfma_f32_16x16x32_bf16 v[92:95], v[184:187], v[226:229], v[92:95]
	v_mfma_f32_16x16x32_bf16 v[88:91], v[192:195], v[226:229], v[88:91]
	v_mfma_f32_16x16x32_bf16 v[76:79], v[184:187], v[234:237], v[76:79]
	v_mfma_f32_16x16x32_bf16 v[72:75], v[192:195], v[234:237], v[72:75]
	v_mfma_f32_16x16x32_bf16 v[124:127], v[188:191], v[214:217], v[124:127]
	v_mfma_f32_16x16x32_bf16 v[120:123], v[196:199], v[214:217], v[120:123]
	v_mfma_f32_16x16x32_bf16 v[108:111], v[188:191], v[222:225], v[108:111]
	v_mfma_f32_16x16x32_bf16 v[104:107], v[196:199], v[222:225], v[104:107]
	v_mfma_f32_16x16x32_bf16 v[92:95], v[188:191], v[230:233], v[92:95]
	v_mfma_f32_16x16x32_bf16 v[88:91], v[196:199], v[230:233], v[88:91]
	v_mfma_f32_16x16x32_bf16 v[76:79], v[188:191], v[238:241], v[76:79]
	v_mfma_f32_16x16x32_bf16 v[72:75], v[196:199], v[238:241], v[72:75]
	s_setprio 0
	s_barrier
	s_add_i32 s46, s64, s20
	v_lshl_add_u64 v[158:159], v[158:159], 0, s[22:23]
	s_mov_b32 m0, s46
	ds_read_b128 v[200:203], v149 offset:49152
	ds_read_b128 v[214:217], v149 offset:50176
	ds_read_b128 v[218:221], v149 offset:51200
	ds_read_b128 v[222:225], v149 offset:52224
	ds_read_b128 v[226:229], v149 offset:53248
	ds_read_b128 v[230:233], v149 offset:54272
	ds_read_b128 v[234:237], v149 offset:55296
	ds_read_b128 v[238:241], v149 offset:56320
	global_load_lds_dwordx4 v[158:159], off
	s_add_i32 m0, s46, 0x2000
	s_add_u32 s44, s44, 0x80080
	v_lshl_add_u64 v[158:159], v[204:205], 0, s[22:23]
	s_addc_u32 s45, s45, 0
	s_add_i32 s46, s65, s20
	global_load_lds_dwordx4 v[158:159], off
	v_lshl_add_u64 v[158:159], s[44:45], 0, v[34:35]
	s_mov_b32 m0, s46
	s_nop 0
	global_load_lds_dwordx4 v[158:159], off
	v_lshl_add_u64 v[158:159], s[44:45], 0, v[14:15]
	s_add_i32 m0, s46, 0x2000
	s_nop 0
	global_load_lds_dwordx4 v[158:159], off
	v_lshl_add_u64 v[158:159], v[242:243], 0, s[22:23]
	s_mov_b32 m0, s48
	s_nop 0
	global_load_lds_dwordx4 v[158:159], off
	v_lshl_add_u64 v[158:159], v[244:245], 0, s[22:23]
	s_mov_b32 m0, s49
	s_nop 0
	global_load_lds_dwordx4 v[158:159], off
	s_waitcnt vmcnt(8)
	s_waitcnt lgkmcnt(0)
	s_barrier
	s_setprio 1
	s_waitcnt lgkmcnt(0)
	v_mfma_f32_16x16x32_bf16 v[68:71], v[162:165], v[200:203], v[68:71]
	v_mfma_f32_16x16x32_bf16 v[64:67], v[170:173], v[200:203], v[64:67]
	v_mfma_f32_16x16x32_bf16 v[52:55], v[162:165], v[218:221], v[52:55]
	v_mfma_f32_16x16x32_bf16 v[48:51], v[170:173], v[218:221], v[48:51]
	v_mfma_f32_16x16x32_bf16 v[36:39], v[162:165], v[226:229], v[36:39]
	v_mfma_f32_16x16x32_bf16 v[30:33], v[170:173], v[226:229], v[30:33]
	v_mfma_f32_16x16x32_bf16 v[18:21], v[162:165], v[234:237], v[18:21]
	v_mfma_f32_16x16x32_bf16 v[10:13], v[170:173], v[234:237], v[10:13]
	v_mfma_f32_16x16x32_bf16 v[68:71], v[166:169], v[214:217], v[68:71]
	v_mfma_f32_16x16x32_bf16 v[64:67], v[174:177], v[214:217], v[64:67]
	v_mfma_f32_16x16x32_bf16 v[52:55], v[166:169], v[222:225], v[52:55]
	v_mfma_f32_16x16x32_bf16 v[48:51], v[174:177], v[222:225], v[48:51]
	v_mfma_f32_16x16x32_bf16 v[36:39], v[166:169], v[230:233], v[36:39]
	v_mfma_f32_16x16x32_bf16 v[30:33], v[174:177], v[230:233], v[30:33]
	v_mfma_f32_16x16x32_bf16 v[18:21], v[166:169], v[238:241], v[18:21]
	v_mfma_f32_16x16x32_bf16 v[10:13], v[174:177], v[238:241], v[10:13]
	s_setprio 0
	s_setprio 1
	v_mfma_f32_16x16x32_bf16 v[60:63], v[184:187], v[200:203], v[60:63]
	v_mfma_f32_16x16x32_bf16 v[56:59], v[192:195], v[200:203], v[56:59]
	v_mfma_f32_16x16x32_bf16 v[44:47], v[184:187], v[218:221], v[44:47]
	v_mfma_f32_16x16x32_bf16 v[40:43], v[192:195], v[218:221], v[40:43]
	v_mfma_f32_16x16x32_bf16 v[26:29], v[184:187], v[226:229], v[26:29]
	v_mfma_f32_16x16x32_bf16 v[22:25], v[192:195], v[226:229], v[22:25]
	v_mfma_f32_16x16x32_bf16 v[6:9], v[184:187], v[234:237], v[6:9]
	v_mfma_f32_16x16x32_bf16 v[2:5], v[192:195], v[234:237], v[2:5]
	v_mfma_f32_16x16x32_bf16 v[60:63], v[188:191], v[214:217], v[60:63]
	v_mfma_f32_16x16x32_bf16 v[56:59], v[196:199], v[214:217], v[56:59]
	v_mfma_f32_16x16x32_bf16 v[44:47], v[188:191], v[222:225], v[44:47]
	v_mfma_f32_16x16x32_bf16 v[40:43], v[196:199], v[222:225], v[40:43]
	v_mfma_f32_16x16x32_bf16 v[26:29], v[188:191], v[230:233], v[26:29]
	v_mfma_f32_16x16x32_bf16 v[22:25], v[196:199], v[230:233], v[22:25]
	v_mfma_f32_16x16x32_bf16 v[6:9], v[188:191], v[238:241], v[6:9]
	v_mfma_f32_16x16x32_bf16 v[2:5], v[196:199], v[238:241], v[2:5]
	s_setprio 0
	s_barrier
	s_add_i32 s61, s61, 2
	s_add_u32 s42, s42, 0x100
	s_addc_u32 s43, s43, 0
	s_add_u32 s55, s55, 0x100
	s_addc_u32 s60, s60, 0
	s_cmp_gt_u32 s61, 29
	s_cbranch_scc0 .LBB0_1664
	s_and_b64 vcc, exec, s[10:11]
	s_cbranch_vccz .LBB0_1667
	s_barrier
